# P8 small-tile GEMM also K-split hand-written (K=4096, 5-step load ring)
# baseline (speedup 1.0000x reference)
; #define LAS __attribute__((address_space(3)))
; #define SG_LOAD(kc, sg) do { _Pragma("unroll") for (int i_ = 0; i_ < 4; ++i_) { const int idx_ = tid + 512 * i_; \
;             ra[sg][i_] = *(const u32x4*)(A + (size_t)(row0 + (idx_ >> 5)) * ld + (kc) * 256 + (idx_ & 31) * 8); if (NC == 64 || i_ < 2) rb[sg][i_] = *(const u32x4*)(Bt + (size_t)(col0 + (idx_ >> 5)) * ld + (kc) * 256 + (idx_ & 31) * 8); } } while (0)
; template <int NC, class Epi>
; __device__ __forceinline__ void small_gemm_phase(LAS unsigned char* lds, const bf16_t* A, const bf16_t* Bt, int K, int ld, int ncolt  , const Epi& E, int first, int nblk, int bid, int tid) {
;     ...
;     for (int u = ub; u < 8 * ncolt; u += nblk) {
;         const int rt = u & 7, ct = u >> 3;
;         const int row0 = NPT + 64 * rt, col0 = NC * ct;
;         u32x4 ra[2][4], rb[2][4];
;     ...
;         SG_LOAD(0, 0); SG_LOAD(1, 1);
;         f32x4 acc0 = {0.f, 0.f, 0.f, 0.f}, acc1 = {0.f, 0.f, 0.f, 0.f};
;         const LAS unsigned char* apl = lds + (16 * mt + fr) * SG_STRIDE + 16 * fq;
;         const LAS unsigned char* bpl = lds + SG_BOFF + ((NC / 2) * nh + fr) * SG_STRIDE + 16 * fq;
; #pragma unroll 1
;         for (int kc = 0; kc < nch; kc += 2) { SG_STEP(kc, 0); SG_STEP(kc + 1, 1); }
.LBB0_1289:
	s_lshl_b32 s8, s21, 6
	s_and_b32 s23, s8, 0x1c0
	s_bitset1_b32 s23, 14
	s_lshl_b32 s8, s21, 2
	s_and_b32 s22, s8, 0x7fffffe0
	s_lshl_b32 s8, s23, 13
	s_add_u32 s24, s58, s8
	s_addc_u32 s25, s59, 0
	s_add_u32 s24, s24, 0x2c00000
	s_addc_u32 s25, s25, 0
	s_lshl_b32 s8, s22, 13
	s_add_u32 s26, s58, s8
	s_addc_u32 s27, s59, 0
	s_add_u32 s26, s26, 0x1700000
	s_addc_u32 s27, s27, 0
	v_and_b32_e32 v241, 15, v192
	v_bfe_u32 v240, v192, 4, 2
	v_lshrrev_b32_e32 v239, 6, v192
	v_lshlrev_b32_e32 v238, 13, v241
	v_lshl_add_u32 v238, v240, 4, v238
	v_lshl_add_u32 v238, v239, 10, v238
	v_mov_b32_e32 v235, v238
	v_add_u32_e32 v234, 0x20000, v238
	v_add_u32_e32 v233, 0x40000, v238
	v_add_u32_e32 v232, 0x60000, v238
	v_mov_b32_e32 v231, v238
	v_add_u32_e32 v230, 0x20000, v238
	v_mov_b32_e32 v0, 0
	v_mov_b32_e32 v1, 0
	v_mov_b32_e32 v2, 0
	v_mov_b32_e32 v3, 0
	v_mov_b32_e32 v4, 0
	v_mov_b32_e32 v5, 0
	v_mov_b32_e32 v6, 0
	v_mov_b32_e32 v7, 0
	v_mov_b32_e32 v8, 0
	v_mov_b32_e32 v9, 0
	v_mov_b32_e32 v10, 0
	v_mov_b32_e32 v11, 0
	v_mov_b32_e32 v12, 0
	v_mov_b32_e32 v13, 0
	v_mov_b32_e32 v14, 0
	v_mov_b32_e32 v15, 0
	v_mov_b32_e32 v16, 0
	v_mov_b32_e32 v17, 0
	v_mov_b32_e32 v18, 0
	v_mov_b32_e32 v19, 0
	v_mov_b32_e32 v20, 0
	v_mov_b32_e32 v21, 0
	v_mov_b32_e32 v22, 0
	v_mov_b32_e32 v23, 0
	v_mov_b32_e32 v24, 0
	v_mov_b32_e32 v25, 0
	v_mov_b32_e32 v26, 0
	v_mov_b32_e32 v27, 0
	v_mov_b32_e32 v28, 0
	v_mov_b32_e32 v29, 0
	v_mov_b32_e32 v30, 0
	v_mov_b32_e32 v31, 0
	global_load_dwordx4 v[32:35], v235, s[24:25] offset:0
	global_load_dwordx4 v[36:39], v234, s[24:25] offset:0
	global_load_dwordx4 v[40:43], v233, s[24:25] offset:0
	global_load_dwordx4 v[44:47], v232, s[24:25] offset:0
	global_load_dwordx4 v[62:65], v231, s[26:27] offset:0
	global_load_dwordx4 v[66:69], v230, s[26:27] offset:0
	global_load_dwordx4 v[70:73], v235, s[24:25] offset:64
	global_load_dwordx4 v[74:77], v234, s[24:25] offset:64
	global_load_dwordx4 v[78:81], v233, s[24:25] offset:64
	global_load_dwordx4 v[82:85], v232, s[24:25] offset:64
	global_load_dwordx4 v[120:123], v231, s[26:27] offset:64
	global_load_dwordx4 v[124:127], v230, s[26:27] offset:64
	global_load_dwordx4 v[128:131], v235, s[24:25] offset:128
	global_load_dwordx4 v[132:135], v234, s[24:25] offset:128
	global_load_dwordx4 v[136:139], v233, s[24:25] offset:128
	global_load_dwordx4 v[140:143], v232, s[24:25] offset:128
	global_load_dwordx4 v[144:147], v231, s[26:27] offset:128
	global_load_dwordx4 v[148:151], v230, s[26:27] offset:128
	global_load_dwordx4 v[152:155], v235, s[24:25] offset:192
	global_load_dwordx4 v[156:159], v234, s[24:25] offset:192
	global_load_dwordx4 v[160:163], v233, s[24:25] offset:192
	global_load_dwordx4 v[164:167], v232, s[24:25] offset:192
	global_load_dwordx4 v[168:171], v231, s[26:27] offset:192
	global_load_dwordx4 v[172:175], v230, s[26:27] offset:192
	global_load_dwordx4 v[176:179], v235, s[24:25] offset:256
	global_load_dwordx4 v[180:183], v234, s[24:25] offset:256
	global_load_dwordx4 v[184:187], v233, s[24:25] offset:256
	global_load_dwordx4 v[188:191], v232, s[24:25] offset:256
	global_load_dwordx4 v[194:197], v231, s[26:27] offset:256
	global_load_dwordx4 v[198:201], v230, s[26:27] offset:256
	s_waitcnt vmcnt(24)
	v_mfma_f32_16x16x32_bf16 v[0:3], v[62:65], v[32:35], v[0:3]
	v_mfma_f32_16x16x32_bf16 v[4:7], v[66:69], v[32:35], v[4:7]
	v_mfma_f32_16x16x32_bf16 v[8:11], v[62:65], v[36:39], v[8:11]
	v_mfma_f32_16x16x32_bf16 v[12:15], v[66:69], v[36:39], v[12:15]
	v_mfma_f32_16x16x32_bf16 v[16:19], v[62:65], v[40:43], v[16:19]
	v_mfma_f32_16x16x32_bf16 v[20:23], v[66:69], v[40:43], v[20:23]
	v_mfma_f32_16x16x32_bf16 v[24:27], v[62:65], v[44:47], v[24:27]
	v_mfma_f32_16x16x32_bf16 v[28:31], v[66:69], v[44:47], v[28:31]
	global_load_dwordx4 v[32:35], v235, s[24:25] offset:320
	global_load_dwordx4 v[36:39], v234, s[24:25] offset:320
	global_load_dwordx4 v[40:43], v233, s[24:25] offset:320
	global_load_dwordx4 v[44:47], v232, s[24:25] offset:320
	global_load_dwordx4 v[62:65], v231, s[26:27] offset:320
	global_load_dwordx4 v[66:69], v230, s[26:27] offset:320
	s_waitcnt vmcnt(24)
	v_mfma_f32_16x16x32_bf16 v[0:3], v[120:123], v[70:73], v[0:3]
	v_mfma_f32_16x16x32_bf16 v[4:7], v[124:127], v[70:73], v[4:7]
	v_mfma_f32_16x16x32_bf16 v[8:11], v[120:123], v[74:77], v[8:11]
	v_mfma_f32_16x16x32_bf16 v[12:15], v[124:127], v[74:77], v[12:15]
	v_mfma_f32_16x16x32_bf16 v[16:19], v[120:123], v[78:81], v[16:19]
	v_mfma_f32_16x16x32_bf16 v[20:23], v[124:127], v[78:81], v[20:23]
	v_mfma_f32_16x16x32_bf16 v[24:27], v[120:123], v[82:85], v[24:27]
	v_mfma_f32_16x16x32_bf16 v[28:31], v[124:127], v[82:85], v[28:31]
	global_load_dwordx4 v[70:73], v235, s[24:25] offset:384
	global_load_dwordx4 v[74:77], v234, s[24:25] offset:384
	global_load_dwordx4 v[78:81], v233, s[24:25] offset:384
	global_load_dwordx4 v[82:85], v232, s[24:25] offset:384
	global_load_dwordx4 v[120:123], v231, s[26:27] offset:384
	global_load_dwordx4 v[124:127], v230, s[26:27] offset:384
	s_waitcnt vmcnt(24)
	v_mfma_f32_16x16x32_bf16 v[0:3], v[144:147], v[128:131], v[0:3]
	v_mfma_f32_16x16x32_bf16 v[4:7], v[148:151], v[128:131], v[4:7]
	v_mfma_f32_16x16x32_bf16 v[8:11], v[144:147], v[132:135], v[8:11]
	v_mfma_f32_16x16x32_bf16 v[12:15], v[148:151], v[132:135], v[12:15]
	v_mfma_f32_16x16x32_bf16 v[16:19], v[144:147], v[136:139], v[16:19]
	v_mfma_f32_16x16x32_bf16 v[20:23], v[148:151], v[136:139], v[20:23]
	v_mfma_f32_16x16x32_bf16 v[24:27], v[144:147], v[140:143], v[24:27]
	v_mfma_f32_16x16x32_bf16 v[28:31], v[148:151], v[140:143], v[28:31]
	global_load_dwordx4 v[128:131], v235, s[24:25] offset:448
	global_load_dwordx4 v[132:135], v234, s[24:25] offset:448
	global_load_dwordx4 v[136:139], v233, s[24:25] offset:448
	global_load_dwordx4 v[140:143], v232, s[24:25] offset:448
	global_load_dwordx4 v[144:147], v231, s[26:27] offset:448
	global_load_dwordx4 v[148:151], v230, s[26:27] offset:448
	s_waitcnt vmcnt(24)
; #define LAS __attribute__((address_space(3)))
; #define SG_LOAD(kc, sg) do { _Pragma("unroll") for (int i_ = 0; i_ < 4; ++i_) { const int idx_ = tid + 512 * i_; \
;             ra[sg][i_] = *(const u32x4*)(A + (size_t)(row0 + (idx_ >> 5)) * ld + (kc) * 256 + (idx_ & 31) * 8); if (NC == 64 || i_ < 2) rb[sg][i_] = *(const u32x4*)(Bt + (size_t)(col0 + (idx_ >> 5)) * ld + (kc) * 256 + (idx_ & 31) * 8); } } while (0)
; template <int NC, class Epi>
; __device__ __forceinline__ void small_gemm_phase(LAS unsigned char* lds, const bf16_t* A, const bf16_t* Bt, int K, int ld, int ncolt  , const Epi& E, int first, int nblk, int bid, int tid) {
;     ...
;         SG_LOAD(0, 0); SG_LOAD(1, 1);
;         f32x4 acc0 = {0.f, 0.f, 0.f, 0.f}, acc1 = {0.f, 0.f, 0.f, 0.f};
;         const LAS unsigned char* apl = lds + (16 * mt + fr) * SG_STRIDE + 16 * fq;
;         const LAS unsigned char* bpl = lds + SG_BOFF + ((NC / 2) * nh + fr) * SG_STRIDE + 16 * fq;
; #pragma unroll 1
;         for (int kc = 0; kc < nch; kc += 2) { SG_STEP(kc, 0); SG_STEP(kc + 1, 1); }
	v_mfma_f32_16x16x32_bf16 v[0:3], v[168:171], v[152:155], v[0:3]
	v_mfma_f32_16x16x32_bf16 v[4:7], v[172:175], v[152:155], v[4:7]
	v_mfma_f32_16x16x32_bf16 v[8:11], v[168:171], v[156:159], v[8:11]
	v_mfma_f32_16x16x32_bf16 v[12:15], v[172:175], v[156:159], v[12:15]
	v_mfma_f32_16x16x32_bf16 v[16:19], v[168:171], v[160:163], v[16:19]
	v_mfma_f32_16x16x32_bf16 v[20:23], v[172:175], v[160:163], v[20:23]
	v_mfma_f32_16x16x32_bf16 v[24:27], v[168:171], v[164:167], v[24:27]
	v_mfma_f32_16x16x32_bf16 v[28:31], v[172:175], v[164:167], v[28:31]
	global_load_dwordx4 v[152:155], v235, s[24:25] offset:512
	global_load_dwordx4 v[156:159], v234, s[24:25] offset:512
	global_load_dwordx4 v[160:163], v233, s[24:25] offset:512
	global_load_dwordx4 v[164:167], v232, s[24:25] offset:512
	global_load_dwordx4 v[168:171], v231, s[26:27] offset:512
	global_load_dwordx4 v[172:175], v230, s[26:27] offset:512
	s_waitcnt vmcnt(24)
	v_mfma_f32_16x16x32_bf16 v[0:3], v[194:197], v[176:179], v[0:3]
	v_mfma_f32_16x16x32_bf16 v[4:7], v[198:201], v[176:179], v[4:7]
	v_mfma_f32_16x16x32_bf16 v[8:11], v[194:197], v[180:183], v[8:11]
	v_mfma_f32_16x16x32_bf16 v[12:15], v[198:201], v[180:183], v[12:15]
	v_mfma_f32_16x16x32_bf16 v[16:19], v[194:197], v[184:187], v[16:19]
	v_mfma_f32_16x16x32_bf16 v[20:23], v[198:201], v[184:187], v[20:23]
	v_mfma_f32_16x16x32_bf16 v[24:27], v[194:197], v[188:191], v[24:27]
	v_mfma_f32_16x16x32_bf16 v[28:31], v[198:201], v[188:191], v[28:31]
	global_load_dwordx4 v[176:179], v235, s[24:25] offset:576
	global_load_dwordx4 v[180:183], v234, s[24:25] offset:576
	global_load_dwordx4 v[184:187], v233, s[24:25] offset:576
	global_load_dwordx4 v[188:191], v232, s[24:25] offset:576
	global_load_dwordx4 v[194:197], v231, s[26:27] offset:576
	global_load_dwordx4 v[198:201], v230, s[26:27] offset:576
	s_waitcnt vmcnt(24)
	v_mfma_f32_16x16x32_bf16 v[0:3], v[62:65], v[32:35], v[0:3]
	v_mfma_f32_16x16x32_bf16 v[4:7], v[66:69], v[32:35], v[4:7]
	v_mfma_f32_16x16x32_bf16 v[8:11], v[62:65], v[36:39], v[8:11]
	v_mfma_f32_16x16x32_bf16 v[12:15], v[66:69], v[36:39], v[12:15]
	v_mfma_f32_16x16x32_bf16 v[16:19], v[62:65], v[40:43], v[16:19]
	v_mfma_f32_16x16x32_bf16 v[20:23], v[66:69], v[40:43], v[20:23]
	v_mfma_f32_16x16x32_bf16 v[24:27], v[62:65], v[44:47], v[24:27]
	v_mfma_f32_16x16x32_bf16 v[28:31], v[66:69], v[44:47], v[28:31]
	global_load_dwordx4 v[32:35], v235, s[24:25] offset:640
	global_load_dwordx4 v[36:39], v234, s[24:25] offset:640
	global_load_dwordx4 v[40:43], v233, s[24:25] offset:640
	global_load_dwordx4 v[44:47], v232, s[24:25] offset:640
	global_load_dwordx4 v[62:65], v231, s[26:27] offset:640
	global_load_dwordx4 v[66:69], v230, s[26:27] offset:640
	s_waitcnt vmcnt(24)
	v_mfma_f32_16x16x32_bf16 v[0:3], v[120:123], v[70:73], v[0:3]
	v_mfma_f32_16x16x32_bf16 v[4:7], v[124:127], v[70:73], v[4:7]
	v_mfma_f32_16x16x32_bf16 v[8:11], v[120:123], v[74:77], v[8:11]
	v_mfma_f32_16x16x32_bf16 v[12:15], v[124:127], v[74:77], v[12:15]
	v_mfma_f32_16x16x32_bf16 v[16:19], v[120:123], v[78:81], v[16:19]
	v_mfma_f32_16x16x32_bf16 v[20:23], v[124:127], v[78:81], v[20:23]
	v_mfma_f32_16x16x32_bf16 v[24:27], v[120:123], v[82:85], v[24:27]
	v_mfma_f32_16x16x32_bf16 v[28:31], v[124:127], v[82:85], v[28:31]
	global_load_dwordx4 v[70:73], v235, s[24:25] offset:704
	global_load_dwordx4 v[74:77], v234, s[24:25] offset:704
	global_load_dwordx4 v[78:81], v233, s[24:25] offset:704
	global_load_dwordx4 v[82:85], v232, s[24:25] offset:704
	global_load_dwordx4 v[120:123], v231, s[26:27] offset:704
	global_load_dwordx4 v[124:127], v230, s[26:27] offset:704
	s_waitcnt vmcnt(24)
	v_mfma_f32_16x16x32_bf16 v[0:3], v[144:147], v[128:131], v[0:3]
	v_mfma_f32_16x16x32_bf16 v[4:7], v[148:151], v[128:131], v[4:7]
	v_mfma_f32_16x16x32_bf16 v[8:11], v[144:147], v[132:135], v[8:11]
	v_mfma_f32_16x16x32_bf16 v[12:15], v[148:151], v[132:135], v[12:15]
	v_mfma_f32_16x16x32_bf16 v[16:19], v[144:147], v[136:139], v[16:19]
	v_mfma_f32_16x16x32_bf16 v[20:23], v[148:151], v[136:139], v[20:23]
	v_mfma_f32_16x16x32_bf16 v[24:27], v[144:147], v[140:143], v[24:27]
	v_mfma_f32_16x16x32_bf16 v[28:31], v[148:151], v[140:143], v[28:31]
	global_load_dwordx4 v[128:131], v235, s[24:25] offset:768
	global_load_dwordx4 v[132:135], v234, s[24:25] offset:768
	global_load_dwordx4 v[136:139], v233, s[24:25] offset:768
	global_load_dwordx4 v[140:143], v232, s[24:25] offset:768
	global_load_dwordx4 v[144:147], v231, s[26:27] offset:768
	global_load_dwordx4 v[148:151], v230, s[26:27] offset:768
	s_waitcnt vmcnt(24)
	v_mfma_f32_16x16x32_bf16 v[0:3], v[168:171], v[152:155], v[0:3]
	v_mfma_f32_16x16x32_bf16 v[4:7], v[172:175], v[152:155], v[4:7]
	v_mfma_f32_16x16x32_bf16 v[8:11], v[168:171], v[156:159], v[8:11]
	v_mfma_f32_16x16x32_bf16 v[12:15], v[172:175], v[156:159], v[12:15]
	v_mfma_f32_16x16x32_bf16 v[16:19], v[168:171], v[160:163], v[16:19]
	v_mfma_f32_16x16x32_bf16 v[20:23], v[172:175], v[160:163], v[20:23]
	v_mfma_f32_16x16x32_bf16 v[24:27], v[168:171], v[164:167], v[24:27]
	v_mfma_f32_16x16x32_bf16 v[28:31], v[172:175], v[164:167], v[28:31]
	global_load_dwordx4 v[152:155], v235, s[24:25] offset:832
	global_load_dwordx4 v[156:159], v234, s[24:25] offset:832
	global_load_dwordx4 v[160:163], v233, s[24:25] offset:832
	global_load_dwordx4 v[164:167], v232, s[24:25] offset:832
	global_load_dwordx4 v[168:171], v231, s[26:27] offset:832
	global_load_dwordx4 v[172:175], v230, s[26:27] offset:832
	s_waitcnt vmcnt(24)
; #define LAS __attribute__((address_space(3)))
; #define SG_LOAD(kc, sg) do { _Pragma("unroll") for (int i_ = 0; i_ < 4; ++i_) { const int idx_ = tid + 512 * i_; \
;             ra[sg][i_] = *(const u32x4*)(A + (size_t)(row0 + (idx_ >> 5)) * ld + (kc) * 256 + (idx_ & 31) * 8); if (NC == 64 || i_ < 2) rb[sg][i_] = *(const u32x4*)(Bt + (size_t)(col0 + (idx_ >> 5)) * ld + (kc) * 256 + (idx_ & 31) * 8); } } while (0)
; template <int NC, class Epi>
; __device__ __forceinline__ void small_gemm_phase(LAS unsigned char* lds, const bf16_t* A, const bf16_t* Bt, int K, int ld, int ncolt  , const Epi& E, int first, int nblk, int bid, int tid) {
;     ...
;         SG_LOAD(0, 0); SG_LOAD(1, 1);
;         f32x4 acc0 = {0.f, 0.f, 0.f, 0.f}, acc1 = {0.f, 0.f, 0.f, 0.f};
;         const LAS unsigned char* apl = lds + (16 * mt + fr) * SG_STRIDE + 16 * fq;
;         const LAS unsigned char* bpl = lds + SG_BOFF + ((NC / 2) * nh + fr) * SG_STRIDE + 16 * fq;
; #pragma unroll 1
;         for (int kc = 0; kc < nch; kc += 2) { SG_STEP(kc, 0); SG_STEP(kc + 1, 1); }
;     ...
;         E(row0 + 16 * mt + fr, col0 + (NC / 2) * nh, fq, acc0, acc1, NC == 64 ? 2 : 1);
	v_mfma_f32_16x16x32_bf16 v[0:3], v[194:197], v[176:179], v[0:3]
	v_mfma_f32_16x16x32_bf16 v[4:7], v[198:201], v[176:179], v[4:7]
	v_mfma_f32_16x16x32_bf16 v[8:11], v[194:197], v[180:183], v[8:11]
	v_mfma_f32_16x16x32_bf16 v[12:15], v[198:201], v[180:183], v[12:15]
	v_mfma_f32_16x16x32_bf16 v[16:19], v[194:197], v[184:187], v[16:19]
	v_mfma_f32_16x16x32_bf16 v[20:23], v[198:201], v[184:187], v[20:23]
	v_mfma_f32_16x16x32_bf16 v[24:27], v[194:197], v[188:191], v[24:27]
	v_mfma_f32_16x16x32_bf16 v[28:31], v[198:201], v[188:191], v[28:31]
	global_load_dwordx4 v[176:179], v235, s[24:25] offset:896
	global_load_dwordx4 v[180:183], v234, s[24:25] offset:896
	global_load_dwordx4 v[184:187], v233, s[24:25] offset:896
	global_load_dwordx4 v[188:191], v232, s[24:25] offset:896
	global_load_dwordx4 v[194:197], v231, s[26:27] offset:896
	global_load_dwordx4 v[198:201], v230, s[26:27] offset:896
	s_waitcnt vmcnt(24)
	v_mfma_f32_16x16x32_bf16 v[0:3], v[62:65], v[32:35], v[0:3]
	v_mfma_f32_16x16x32_bf16 v[4:7], v[66:69], v[32:35], v[4:7]
	v_mfma_f32_16x16x32_bf16 v[8:11], v[62:65], v[36:39], v[8:11]
	v_mfma_f32_16x16x32_bf16 v[12:15], v[66:69], v[36:39], v[12:15]
	v_mfma_f32_16x16x32_bf16 v[16:19], v[62:65], v[40:43], v[16:19]
	v_mfma_f32_16x16x32_bf16 v[20:23], v[66:69], v[40:43], v[20:23]
	v_mfma_f32_16x16x32_bf16 v[24:27], v[62:65], v[44:47], v[24:27]
	v_mfma_f32_16x16x32_bf16 v[28:31], v[66:69], v[44:47], v[28:31]
	global_load_dwordx4 v[32:35], v235, s[24:25] offset:960
	global_load_dwordx4 v[36:39], v234, s[24:25] offset:960
	global_load_dwordx4 v[40:43], v233, s[24:25] offset:960
	global_load_dwordx4 v[44:47], v232, s[24:25] offset:960
	global_load_dwordx4 v[62:65], v231, s[26:27] offset:960
	global_load_dwordx4 v[66:69], v230, s[26:27] offset:960
	s_waitcnt vmcnt(24)
	v_mfma_f32_16x16x32_bf16 v[0:3], v[120:123], v[70:73], v[0:3]
	v_mfma_f32_16x16x32_bf16 v[4:7], v[124:127], v[70:73], v[4:7]
	v_mfma_f32_16x16x32_bf16 v[8:11], v[120:123], v[74:77], v[8:11]
	v_mfma_f32_16x16x32_bf16 v[12:15], v[124:127], v[74:77], v[12:15]
	v_mfma_f32_16x16x32_bf16 v[16:19], v[120:123], v[78:81], v[16:19]
	v_mfma_f32_16x16x32_bf16 v[20:23], v[124:127], v[78:81], v[20:23]
	v_mfma_f32_16x16x32_bf16 v[24:27], v[120:123], v[82:85], v[24:27]
	v_mfma_f32_16x16x32_bf16 v[28:31], v[124:127], v[82:85], v[28:31]
	s_waitcnt vmcnt(18)
	v_mfma_f32_16x16x32_bf16 v[0:3], v[144:147], v[128:131], v[0:3]
	v_mfma_f32_16x16x32_bf16 v[4:7], v[148:151], v[128:131], v[4:7]
	v_mfma_f32_16x16x32_bf16 v[8:11], v[144:147], v[132:135], v[8:11]
	v_mfma_f32_16x16x32_bf16 v[12:15], v[148:151], v[132:135], v[12:15]
	v_mfma_f32_16x16x32_bf16 v[16:19], v[144:147], v[136:139], v[16:19]
	v_mfma_f32_16x16x32_bf16 v[20:23], v[148:151], v[136:139], v[20:23]
	v_mfma_f32_16x16x32_bf16 v[24:27], v[144:147], v[140:143], v[24:27]
	v_mfma_f32_16x16x32_bf16 v[28:31], v[148:151], v[140:143], v[28:31]
	s_waitcnt vmcnt(12)
	v_mfma_f32_16x16x32_bf16 v[0:3], v[168:171], v[152:155], v[0:3]
	v_mfma_f32_16x16x32_bf16 v[4:7], v[172:175], v[152:155], v[4:7]
	v_mfma_f32_16x16x32_bf16 v[8:11], v[168:171], v[156:159], v[8:11]
	v_mfma_f32_16x16x32_bf16 v[12:15], v[172:175], v[156:159], v[12:15]
	v_mfma_f32_16x16x32_bf16 v[16:19], v[168:171], v[160:163], v[16:19]
	v_mfma_f32_16x16x32_bf16 v[20:23], v[172:175], v[160:163], v[20:23]
	v_mfma_f32_16x16x32_bf16 v[24:27], v[168:171], v[164:167], v[24:27]
	v_mfma_f32_16x16x32_bf16 v[28:31], v[172:175], v[164:167], v[28:31]
	s_waitcnt vmcnt(6)
	v_mfma_f32_16x16x32_bf16 v[0:3], v[194:197], v[176:179], v[0:3]
	v_mfma_f32_16x16x32_bf16 v[4:7], v[198:201], v[176:179], v[4:7]
	v_mfma_f32_16x16x32_bf16 v[8:11], v[194:197], v[180:183], v[8:11]
	v_mfma_f32_16x16x32_bf16 v[12:15], v[198:201], v[180:183], v[12:15]
	v_mfma_f32_16x16x32_bf16 v[16:19], v[194:197], v[184:187], v[16:19]
	v_mfma_f32_16x16x32_bf16 v[20:23], v[198:201], v[184:187], v[20:23]
	v_mfma_f32_16x16x32_bf16 v[24:27], v[194:197], v[188:191], v[24:27]
	v_mfma_f32_16x16x32_bf16 v[28:31], v[198:201], v[188:191], v[28:31]
	s_waitcnt vmcnt(0)
	v_mfma_f32_16x16x32_bf16 v[0:3], v[62:65], v[32:35], v[0:3]
	v_mfma_f32_16x16x32_bf16 v[4:7], v[66:69], v[32:35], v[4:7]
	v_mfma_f32_16x16x32_bf16 v[8:11], v[62:65], v[36:39], v[8:11]
	v_mfma_f32_16x16x32_bf16 v[12:15], v[66:69], v[36:39], v[12:15]
	v_mfma_f32_16x16x32_bf16 v[16:19], v[62:65], v[40:43], v[16:19]
	v_mfma_f32_16x16x32_bf16 v[20:23], v[66:69], v[40:43], v[20:23]
	v_mfma_f32_16x16x32_bf16 v[24:27], v[62:65], v[44:47], v[24:27]
	v_mfma_f32_16x16x32_bf16 v[28:31], v[66:69], v[44:47], v[28:31]
	v_lshlrev_b32_e32 v237, 4, v192
	v_mul_u32_u24_e32 v236, 0x1c00, v239
	v_add_u32_e32 v236, v237, v236
	s_nop 15
	s_nop 15
	ds_write_b128 v236, v[0:3] offset:0
	ds_write_b128 v236, v[4:7] offset:1024
	ds_write_b128 v236, v[8:11] offset:2048
	ds_write_b128 v236, v[12:15] offset:3072
	ds_write_b128 v236, v[16:19] offset:4096
	ds_write_b128 v236, v[20:23] offset:5120
	ds_write_b128 v236, v[24:27] offset:6144
	ds_write_b128 v236, v[28:31] offset:7168
	s_waitcnt lgkmcnt(0)
	s_barrier
	ds_read_b128 v[32:35], v237 offset:0
	ds_read_b128 v[36:39], v237 offset:8192
	ds_read_b128 v[40:43], v237 offset:16384
	ds_read_b128 v[44:47], v237 offset:24576
	ds_read_b128 v[62:65], v237 offset:32768
	ds_read_b128 v[66:69], v237 offset:40960
	ds_read_b128 v[70:73], v237 offset:49152
	ds_read_b128 v[74:77], v237 offset:57344
	s_waitcnt lgkmcnt(6)
	v_pk_add_f32 v[48:49], v[32:33], v[36:37]
	v_pk_add_f32 v[50:51], v[34:35], v[38:39]
	s_waitcnt lgkmcnt(5)
	v_pk_add_f32 v[48:49], v[48:49], v[40:41]
	v_pk_add_f32 v[50:51], v[50:51], v[42:43]
	s_waitcnt lgkmcnt(4)
	v_pk_add_f32 v[48:49], v[48:49], v[44:45]
	v_pk_add_f32 v[50:51], v[50:51], v[46:47]
	s_waitcnt lgkmcnt(3)
	v_pk_add_f32 v[48:49], v[48:49], v[62:63]
	v_pk_add_f32 v[50:51], v[50:51], v[64:65]
	s_waitcnt lgkmcnt(2)
	v_pk_add_f32 v[48:49], v[48:49], v[66:67]
	v_pk_add_f32 v[50:51], v[50:51], v[68:69]
	s_waitcnt lgkmcnt(1)
	v_pk_add_f32 v[48:49], v[48:49], v[70:71]
	v_pk_add_f32 v[50:51], v[50:51], v[72:73]
	s_waitcnt lgkmcnt(0)
	v_pk_add_f32 v[48:49], v[48:49], v[74:75]
	v_pk_add_f32 v[50:51], v[50:51], v[76:77]
	s_barrier
	s_branch .LBB0_1288
